# convert_weights pool-fold K loop (inside down-proj phase) rewritten with rolling 16-deep prefetch (hipcc had 2 loads in flight; it was the layer-1 down-proj critical path)
# speedup vs baseline: 1.1414x; 1.0318x over previous
.LBB0_522:
	s_or_b64 exec, exec, s[16:17]
	v_ashrrev_i32_e32 v13, 31, v12
	v_lshlrev_b64 v[14:15], 12, v[12:13]
	v_lshl_add_u64 v[14:15], v[10:11], 0, v[14:15]
	s_mov_b64 s[0:1], 0x200000
	v_mov_b32_e32 v20, 0
	v_lshl_add_u64 v[14:15], v[14:15], 0, s[0:1]
	s_mov_b64 s[14:15], 0
	s_mov_b32 s8, s36
	v_mov_b32_e32 v21, v20
	v_mov_b32_e32 v18, v20
	v_mov_b32_e32 v19, v20
	s_waitcnt lgkmcnt(0)
	s_barrier
	s_mov_b32 s1, 0
	s_mov_b32 s0, 0x400000
	v_lshl_add_u64 v[58:59], v[14:15], 0, s[0:1]
	v_mov_b64_e32 v[56:57], v[58:59]
	global_load_dword v40, v[56:57], off
	global_load_dword v41, v[56:57], off offset:2048
	s_mov_b32 s0, 0x1000
	v_lshl_add_u64 v[56:57], v[58:59], 0, s[0:1]
	global_load_dword v42, v[56:57], off
	global_load_dword v43, v[56:57], off offset:2048
	s_mov_b32 s0, 0x2000
	v_lshl_add_u64 v[56:57], v[58:59], 0, s[0:1]
	global_load_dword v44, v[56:57], off
	global_load_dword v45, v[56:57], off offset:2048
	s_mov_b32 s0, 0x3000
	v_lshl_add_u64 v[56:57], v[58:59], 0, s[0:1]
	global_load_dword v46, v[56:57], off
	global_load_dword v47, v[56:57], off offset:2048
	s_mov_b32 s0, 0x4000
	v_lshl_add_u64 v[56:57], v[58:59], 0, s[0:1]
	global_load_dword v48, v[56:57], off
	global_load_dword v49, v[56:57], off offset:2048
	s_mov_b32 s0, 0x5000
	v_lshl_add_u64 v[56:57], v[58:59], 0, s[0:1]
	global_load_dword v50, v[56:57], off
	global_load_dword v51, v[56:57], off offset:2048
	s_mov_b32 s0, 0x6000
	v_lshl_add_u64 v[56:57], v[58:59], 0, s[0:1]
	global_load_dword v52, v[56:57], off
	global_load_dword v53, v[56:57], off offset:2048
	s_mov_b32 s0, 0x7000
	v_lshl_add_u64 v[56:57], v[58:59], 0, s[0:1]
	global_load_dword v54, v[56:57], off
	global_load_dword v55, v[56:57], off offset:2048
.LBB0_523:
	s_add_u32 s14, s14, 0x8000
	s_addc_u32 s15, s15, 0
	v_lshl_add_u64 v[76:77], v[58:59], 0, s[14:15]
	v_mov_b32_e32 v23, s8
	ds_read2_b32 v[60:61], v23 offset0:0 offset1:1
	ds_read2_b32 v[62:63], v23 offset0:2 offset1:3
	ds_read2_b32 v[64:65], v23 offset0:4 offset1:5
	ds_read2_b32 v[66:67], v23 offset0:6 offset1:7
	ds_read2_b32 v[68:69], v23 offset0:128 offset1:129
	ds_read2_b32 v[70:71], v23 offset0:130 offset1:131
	ds_read2_b32 v[72:73], v23 offset0:132 offset1:133
	ds_read2_b32 v[74:75], v23 offset0:134 offset1:135
	s_add_i32 s8, s8, 32
	s_waitcnt lgkmcnt(0)
	s_waitcnt vmcnt(15)
	v_fma_f32 v20, v40, v60, v20
	v_fma_f32 v21, v40, v68, v21
	v_mov_b64_e32 v[56:57], v[76:77]
	global_load_dword v40, v[56:57], off
	s_waitcnt vmcnt(15)
	v_fma_f32 v18, v41, v60, v18
	v_fma_f32 v19, v41, v68, v19
	global_load_dword v41, v[56:57], off offset:2048
	s_waitcnt vmcnt(15)
	v_fma_f32 v20, v42, v61, v20
	v_fma_f32 v21, v42, v69, v21
	s_mov_b32 s0, 0x1000
	v_lshl_add_u64 v[56:57], v[76:77], 0, s[0:1]
	global_load_dword v42, v[56:57], off
	s_waitcnt vmcnt(15)
	v_fma_f32 v18, v43, v61, v18
	v_fma_f32 v19, v43, v69, v19
	global_load_dword v43, v[56:57], off offset:2048
	s_waitcnt vmcnt(15)
	v_fma_f32 v20, v44, v62, v20
	v_fma_f32 v21, v44, v70, v21
	s_mov_b32 s0, 0x2000
	v_lshl_add_u64 v[56:57], v[76:77], 0, s[0:1]
	global_load_dword v44, v[56:57], off
	s_waitcnt vmcnt(15)
	v_fma_f32 v18, v45, v62, v18
	v_fma_f32 v19, v45, v70, v19
	global_load_dword v45, v[56:57], off offset:2048
	s_waitcnt vmcnt(15)
	v_fma_f32 v20, v46, v63, v20
	v_fma_f32 v21, v46, v71, v21
	s_mov_b32 s0, 0x3000
	v_lshl_add_u64 v[56:57], v[76:77], 0, s[0:1]
	global_load_dword v46, v[56:57], off
	s_waitcnt vmcnt(15)
	v_fma_f32 v18, v47, v63, v18
	v_fma_f32 v19, v47, v71, v19
	global_load_dword v47, v[56:57], off offset:2048
	s_waitcnt vmcnt(15)
	v_fma_f32 v20, v48, v64, v20
	v_fma_f32 v21, v48, v72, v21
	s_mov_b32 s0, 0x4000
	v_lshl_add_u64 v[56:57], v[76:77], 0, s[0:1]
	global_load_dword v48, v[56:57], off
	s_waitcnt vmcnt(15)
	v_fma_f32 v18, v49, v64, v18
	v_fma_f32 v19, v49, v72, v19
	global_load_dword v49, v[56:57], off offset:2048
	s_waitcnt vmcnt(15)
	v_fma_f32 v20, v50, v65, v20
	v_fma_f32 v21, v50, v73, v21
	s_mov_b32 s0, 0x5000
	v_lshl_add_u64 v[56:57], v[76:77], 0, s[0:1]
	global_load_dword v50, v[56:57], off
	s_waitcnt vmcnt(15)
	v_fma_f32 v18, v51, v65, v18
	v_fma_f32 v19, v51, v73, v19
	global_load_dword v51, v[56:57], off offset:2048
	s_waitcnt vmcnt(15)
	v_fma_f32 v20, v52, v66, v20
	v_fma_f32 v21, v52, v74, v21
	s_mov_b32 s0, 0x6000
	v_lshl_add_u64 v[56:57], v[76:77], 0, s[0:1]
	global_load_dword v52, v[56:57], off
	s_waitcnt vmcnt(15)
	v_fma_f32 v18, v53, v66, v18
	v_fma_f32 v19, v53, v74, v19
	global_load_dword v53, v[56:57], off offset:2048
	s_waitcnt vmcnt(15)
	v_fma_f32 v20, v54, v67, v20
	v_fma_f32 v21, v54, v75, v21
	s_mov_b32 s0, 0x7000
	v_lshl_add_u64 v[56:57], v[76:77], 0, s[0:1]
	global_load_dword v54, v[56:57], off
	s_waitcnt vmcnt(15)
	v_fma_f32 v18, v55, v67, v18
	v_fma_f32 v19, v55, v75, v19
	global_load_dword v55, v[56:57], off offset:2048
	s_cmp_eq_u32 s14, 0x78000
	s_cbranch_scc0 .LBB0_523
	v_mov_b32_e32 v23, s8
	ds_read2_b32 v[60:61], v23 offset0:0 offset1:1
	ds_read2_b32 v[62:63], v23 offset0:2 offset1:3
	ds_read2_b32 v[64:65], v23 offset0:4 offset1:5
	ds_read2_b32 v[66:67], v23 offset0:6 offset1:7
	ds_read2_b32 v[68:69], v23 offset0:128 offset1:129
	ds_read2_b32 v[70:71], v23 offset0:130 offset1:131
	ds_read2_b32 v[72:73], v23 offset0:132 offset1:133
	ds_read2_b32 v[74:75], v23 offset0:134 offset1:135
	s_add_i32 s8, s8, 32
	s_waitcnt lgkmcnt(0)
	s_waitcnt vmcnt(15)
	v_fma_f32 v20, v40, v60, v20
	v_fma_f32 v21, v40, v68, v21
	s_waitcnt vmcnt(14)
	v_fma_f32 v18, v41, v60, v18
	v_fma_f32 v19, v41, v68, v19
	s_waitcnt vmcnt(13)
	v_fma_f32 v20, v42, v61, v20
	v_fma_f32 v21, v42, v69, v21
	s_waitcnt vmcnt(12)
	v_fma_f32 v18, v43, v61, v18
	v_fma_f32 v19, v43, v69, v19
	s_waitcnt vmcnt(11)
	v_fma_f32 v20, v44, v62, v20
	v_fma_f32 v21, v44, v70, v21
	s_waitcnt vmcnt(10)
	v_fma_f32 v18, v45, v62, v18
	v_fma_f32 v19, v45, v70, v19
	s_waitcnt vmcnt(9)
	v_fma_f32 v20, v46, v63, v20
	v_fma_f32 v21, v46, v71, v21
	s_waitcnt vmcnt(8)
	v_fma_f32 v18, v47, v63, v18
	v_fma_f32 v19, v47, v71, v19
	s_waitcnt vmcnt(7)
	v_fma_f32 v20, v48, v64, v20
	v_fma_f32 v21, v48, v72, v21
	s_waitcnt vmcnt(6)
	v_fma_f32 v18, v49, v64, v18
	v_fma_f32 v19, v49, v72, v19
	s_waitcnt vmcnt(5)
	v_fma_f32 v20, v50, v65, v20
	v_fma_f32 v21, v50, v73, v21
	s_waitcnt vmcnt(4)
	v_fma_f32 v18, v51, v65, v18
	v_fma_f32 v19, v51, v73, v19
	s_waitcnt vmcnt(3)
	v_fma_f32 v20, v52, v66, v20
	v_fma_f32 v21, v52, v74, v21
	s_waitcnt vmcnt(2)
	v_fma_f32 v18, v53, v66, v18
	v_fma_f32 v19, v53, v74, v19
	s_waitcnt vmcnt(1)
	v_fma_f32 v20, v54, v67, v20
	v_fma_f32 v21, v54, v75, v21
	s_waitcnt vmcnt(0)
	v_fma_f32 v18, v55, v67, v18
	v_fma_f32 v19, v55, v75, v19
	v_lshlrev_b64 v[12:13], 1, v[12:13]
	v_lshl_add_u64 v[14:15], v[6:7], 0, v[12:13]
	s_lshl_b32 s86, s86, 1
	v_cvt_pk_bf16_f32 v16, v20, v21
	v_lshl_add_u64 v[14:15], v[14:15], 0, s[86:87]
	v_lshl_add_u64 v[12:13], v[8:9], 0, v[12:13]
	s_add_i32 s4, s4, s5
	global_store_dword v[14:15], v16, off offset:1024
	v_cvt_pk_bf16_f32 v14, v18, v19
	v_lshl_add_u64 v[12:13], v[12:13], 0, s[86:87]
	s_cmpk_gt_i32 s4, 0xff
	global_store_dword v[12:13], v14, off offset:1024
	s_cbranch_scc0 .LBB0_518

.LBB0_689:
	s_or_b64 exec, exec, s[16:17]
	v_ashrrev_i32_e32 v13, 31, v12
	v_lshlrev_b64 v[14:15], 12, v[12:13]
	v_lshl_add_u64 v[14:15], v[10:11], 0, v[14:15]
	s_mov_b64 s[0:1], 0x200000
	v_mov_b32_e32 v20, 0
	v_lshl_add_u64 v[14:15], v[14:15], 0, s[0:1]
	s_mov_b64 s[14:15], 0
	s_mov_b32 s4, s36
	v_mov_b32_e32 v21, v20
	v_mov_b32_e32 v18, v20
	v_mov_b32_e32 v19, v20
	s_waitcnt lgkmcnt(0)
	s_barrier
	s_mov_b32 s1, 0
	s_mov_b32 s0, 0x400000
	v_lshl_add_u64 v[58:59], v[14:15], 0, s[0:1]
	v_mov_b64_e32 v[56:57], v[58:59]
	global_load_dword v40, v[56:57], off
	global_load_dword v41, v[56:57], off offset:2048
	s_mov_b32 s0, 0x1000
	v_lshl_add_u64 v[56:57], v[58:59], 0, s[0:1]
	global_load_dword v42, v[56:57], off
	global_load_dword v43, v[56:57], off offset:2048
	s_mov_b32 s0, 0x2000
	v_lshl_add_u64 v[56:57], v[58:59], 0, s[0:1]
	global_load_dword v44, v[56:57], off
	global_load_dword v45, v[56:57], off offset:2048
	s_mov_b32 s0, 0x3000
	v_lshl_add_u64 v[56:57], v[58:59], 0, s[0:1]
	global_load_dword v46, v[56:57], off
	global_load_dword v47, v[56:57], off offset:2048
	s_mov_b32 s0, 0x4000
	v_lshl_add_u64 v[56:57], v[58:59], 0, s[0:1]
	global_load_dword v48, v[56:57], off
	global_load_dword v49, v[56:57], off offset:2048
	s_mov_b32 s0, 0x5000
	v_lshl_add_u64 v[56:57], v[58:59], 0, s[0:1]
	global_load_dword v50, v[56:57], off
	global_load_dword v51, v[56:57], off offset:2048
	s_mov_b32 s0, 0x6000
	v_lshl_add_u64 v[56:57], v[58:59], 0, s[0:1]
	global_load_dword v52, v[56:57], off
	global_load_dword v53, v[56:57], off offset:2048
	s_mov_b32 s0, 0x7000
	v_lshl_add_u64 v[56:57], v[58:59], 0, s[0:1]
	global_load_dword v54, v[56:57], off
	global_load_dword v55, v[56:57], off offset:2048
.LBB0_690:
	s_add_u32 s14, s14, 0x8000
	s_addc_u32 s15, s15, 0
	v_lshl_add_u64 v[76:77], v[58:59], 0, s[14:15]
	v_mov_b32_e32 v23, s4
	ds_read2_b32 v[60:61], v23 offset0:0 offset1:1
	ds_read2_b32 v[62:63], v23 offset0:2 offset1:3
	ds_read2_b32 v[64:65], v23 offset0:4 offset1:5
	ds_read2_b32 v[66:67], v23 offset0:6 offset1:7
	ds_read2_b32 v[68:69], v23 offset0:128 offset1:129
	ds_read2_b32 v[70:71], v23 offset0:130 offset1:131
	ds_read2_b32 v[72:73], v23 offset0:132 offset1:133
	ds_read2_b32 v[74:75], v23 offset0:134 offset1:135
	s_add_i32 s4, s4, 32
	s_waitcnt lgkmcnt(0)
	s_waitcnt vmcnt(15)
	v_fma_f32 v20, v40, v60, v20
	v_fma_f32 v21, v40, v68, v21
	v_mov_b64_e32 v[56:57], v[76:77]
	global_load_dword v40, v[56:57], off
	s_waitcnt vmcnt(15)
	v_fma_f32 v18, v41, v60, v18
	v_fma_f32 v19, v41, v68, v19
	global_load_dword v41, v[56:57], off offset:2048
	s_waitcnt vmcnt(15)
	v_fma_f32 v20, v42, v61, v20
	v_fma_f32 v21, v42, v69, v21
	s_mov_b32 s0, 0x1000
	v_lshl_add_u64 v[56:57], v[76:77], 0, s[0:1]
	global_load_dword v42, v[56:57], off
	s_waitcnt vmcnt(15)
	v_fma_f32 v18, v43, v61, v18
	v_fma_f32 v19, v43, v69, v19
	global_load_dword v43, v[56:57], off offset:2048
	s_waitcnt vmcnt(15)
	v_fma_f32 v20, v44, v62, v20
	v_fma_f32 v21, v44, v70, v21
	s_mov_b32 s0, 0x2000
	v_lshl_add_u64 v[56:57], v[76:77], 0, s[0:1]
	global_load_dword v44, v[56:57], off
	s_waitcnt vmcnt(15)
	v_fma_f32 v18, v45, v62, v18
	v_fma_f32 v19, v45, v70, v19
	global_load_dword v45, v[56:57], off offset:2048
	s_waitcnt vmcnt(15)
	v_fma_f32 v20, v46, v63, v20
	v_fma_f32 v21, v46, v71, v21
	s_mov_b32 s0, 0x3000
	v_lshl_add_u64 v[56:57], v[76:77], 0, s[0:1]
	global_load_dword v46, v[56:57], off
	s_waitcnt vmcnt(15)
	v_fma_f32 v18, v47, v63, v18
	v_fma_f32 v19, v47, v71, v19
	global_load_dword v47, v[56:57], off offset:2048
	s_waitcnt vmcnt(15)
	v_fma_f32 v20, v48, v64, v20
	v_fma_f32 v21, v48, v72, v21
	s_mov_b32 s0, 0x4000
	v_lshl_add_u64 v[56:57], v[76:77], 0, s[0:1]
	global_load_dword v48, v[56:57], off
	s_waitcnt vmcnt(15)
	v_fma_f32 v18, v49, v64, v18
	v_fma_f32 v19, v49, v72, v19
	global_load_dword v49, v[56:57], off offset:2048
	s_waitcnt vmcnt(15)
	v_fma_f32 v20, v50, v65, v20
	v_fma_f32 v21, v50, v73, v21
	s_mov_b32 s0, 0x5000
	v_lshl_add_u64 v[56:57], v[76:77], 0, s[0:1]
	global_load_dword v50, v[56:57], off
	s_waitcnt vmcnt(15)
	v_fma_f32 v18, v51, v65, v18
	v_fma_f32 v19, v51, v73, v19
	global_load_dword v51, v[56:57], off offset:2048
	s_waitcnt vmcnt(15)
	v_fma_f32 v20, v52, v66, v20
	v_fma_f32 v21, v52, v74, v21
	s_mov_b32 s0, 0x6000
	v_lshl_add_u64 v[56:57], v[76:77], 0, s[0:1]
	global_load_dword v52, v[56:57], off
	s_waitcnt vmcnt(15)
	v_fma_f32 v18, v53, v66, v18
	v_fma_f32 v19, v53, v74, v19
	global_load_dword v53, v[56:57], off offset:2048
	s_waitcnt vmcnt(15)
	v_fma_f32 v20, v54, v67, v20
	v_fma_f32 v21, v54, v75, v21
	s_mov_b32 s0, 0x7000
	v_lshl_add_u64 v[56:57], v[76:77], 0, s[0:1]
	global_load_dword v54, v[56:57], off
	s_waitcnt vmcnt(15)
	v_fma_f32 v18, v55, v67, v18
	v_fma_f32 v19, v55, v75, v19
	global_load_dword v55, v[56:57], off offset:2048
	s_cmp_eq_u32 s14, 0x78000
	s_cbranch_scc0 .LBB0_690
	v_mov_b32_e32 v23, s4
	ds_read2_b32 v[60:61], v23 offset0:0 offset1:1
	ds_read2_b32 v[62:63], v23 offset0:2 offset1:3
	ds_read2_b32 v[64:65], v23 offset0:4 offset1:5
	ds_read2_b32 v[66:67], v23 offset0:6 offset1:7
	ds_read2_b32 v[68:69], v23 offset0:128 offset1:129
	ds_read2_b32 v[70:71], v23 offset0:130 offset1:131
	ds_read2_b32 v[72:73], v23 offset0:132 offset1:133
	ds_read2_b32 v[74:75], v23 offset0:134 offset1:135
	s_add_i32 s4, s4, 32
	s_waitcnt lgkmcnt(0)
	s_waitcnt vmcnt(15)
	v_fma_f32 v20, v40, v60, v20
	v_fma_f32 v21, v40, v68, v21
	s_waitcnt vmcnt(14)
	v_fma_f32 v18, v41, v60, v18
	v_fma_f32 v19, v41, v68, v19
	s_waitcnt vmcnt(13)
	v_fma_f32 v20, v42, v61, v20
	v_fma_f32 v21, v42, v69, v21
	s_waitcnt vmcnt(12)
	v_fma_f32 v18, v43, v61, v18
	v_fma_f32 v19, v43, v69, v19
	s_waitcnt vmcnt(11)
	v_fma_f32 v20, v44, v62, v20
	v_fma_f32 v21, v44, v70, v21
	s_waitcnt vmcnt(10)
	v_fma_f32 v18, v45, v62, v18
	v_fma_f32 v19, v45, v70, v19
	s_waitcnt vmcnt(9)
	v_fma_f32 v20, v46, v63, v20
	v_fma_f32 v21, v46, v71, v21
	s_waitcnt vmcnt(8)
	v_fma_f32 v18, v47, v63, v18
	v_fma_f32 v19, v47, v71, v19
	s_waitcnt vmcnt(7)
	v_fma_f32 v20, v48, v64, v20
	v_fma_f32 v21, v48, v72, v21
	s_waitcnt vmcnt(6)
	v_fma_f32 v18, v49, v64, v18
	v_fma_f32 v19, v49, v72, v19
	s_waitcnt vmcnt(5)
	v_fma_f32 v20, v50, v65, v20
	v_fma_f32 v21, v50, v73, v21
	s_waitcnt vmcnt(4)
	v_fma_f32 v18, v51, v65, v18
	v_fma_f32 v19, v51, v73, v19
	s_waitcnt vmcnt(3)
	v_fma_f32 v20, v52, v66, v20
	v_fma_f32 v21, v52, v74, v21
	s_waitcnt vmcnt(2)
	v_fma_f32 v18, v53, v66, v18
	v_fma_f32 v19, v53, v74, v19
	s_waitcnt vmcnt(1)
	v_fma_f32 v20, v54, v67, v20
	v_fma_f32 v21, v54, v75, v21
	s_waitcnt vmcnt(0)
	v_fma_f32 v18, v55, v67, v18
	v_fma_f32 v19, v55, v75, v19
	v_lshlrev_b64 v[12:13], 1, v[12:13]
	v_lshl_add_u64 v[14:15], v[6:7], 0, v[12:13]
	s_lshl_b32 s86, s86, 1
	v_cvt_pk_bf16_f32 v16, v20, v21
	v_lshl_add_u64 v[14:15], v[14:15], 0, s[86:87]
	v_lshl_add_u64 v[12:13], v[8:9], 0, v[12:13]
	s_add_i32 s34, s34, s30
	global_store_dword v[14:15], v16, off offset:1024
	v_cvt_pk_bf16_f32 v14, v18, v19
	v_lshl_add_u64 v[12:13], v[12:13], 0, s[86:87]
	s_cmpk_gt_i32 s34, 0xff
	global_store_dword v[12:13], v14, off offset:1024
	s_cbranch_scc0 .LBB0_685
